# window-attention q-tile loop re-emitted by hand (3-deep K fragment ring, 2-chunk V ring, in-place P packing, grouped exp) on top of v32
# speedup vs baseline: 1.0176x; 1.0056x over previous
; #define LAS __attribute__((address_space(3)))
; __device__ __forceinline__ void mixer_unit(const Params& p, LAS unsigned char* lds, int tile, int layer, int wave_s) {
;     ...
;                 const int beta0 = a >> 5, qq = (a & 31) + rho;
;                 f32x4 S[9][2];
; #pragma unroll
;                 for (int c = 0; c < 9; ++c) {
;                     const int beta = beta0 + c;
; #pragma unroll
;                     for (int w = 0; w < 2; ++w) {
;                         const int sl = 32 * beta + 16 * w + rho;
;                         const bf16x8 k0 = *(const LAS bf16x8*)(lds + L_K + sl * 128 + ((g ^ (sl & 7)) << 4));
;                         const bf16x8 k1 = *(const LAS bf16x8*)(lds + L_K + sl * 128 + (((4 + g) ^ (sl & 7)) << 4));
;                         f32x4 acc = (f32x4){0.f, 0.f, 0.f, 0.f};
;                         acc = __builtin_amdgcn_mfma_f32_16x16x32_bf16(k0, qf[0], acc, 0, 0, 0);
;                         acc = __builtin_amdgcn_mfma_f32_16x16x32_bf16(k1, qf[1], acc, 0, 0, 0);
;                         S[c][w] = acc;
;                     }
;                     if (c == 0) {
; #pragma unroll
;                         for (int w = 0; w < 2; ++w)
; #pragma unroll
;                             for (int r = 0; r < 4; ++r) S[c][w][r] = (8 * g + 4 * w + r < qq) ? -INFINITY : S[c][w][r];
;                     }
;                     if (c == 8) {
; #pragma unroll
;                         for (int w = 0; w < 2; ++w)
; #pragma unroll
;                             for (int r = 0; r < 4; ++r) S[c][w][r] = (8 * g + 4 * w + r > qq) ? -INFINITY : S[c][w][r];
;                     }
;                 }
.Lwa_q_ready:
	v_mov_b64_e32 v[126:127], v[50:51]
	v_add_lshl_u32 v2, v3, v2, 1
	v_mov_b64_e32 v[124:125], v[48:49]
	v_mov_b64_e32 v[130:131], v[46:47]
	global_load_dwordx4 v[48:51], v2, s[16:17]
	v_or_b32_e32 v2, 64, v2
	s_and_b32 s37, s33, 0xfffff000
	v_mov_b64_e32 v[128:129], v[44:45]
	global_load_dwordx4 v[44:47], v2, s[16:17]
	v_add_u32_e32 v252, s37, v155
	v_add_u32_e32 v253, v252, v143
	v_add_u32_e32 v252, v252, v142
	v_and_or_b32 v3, s10, 16, v138
	ds_read_b128 v[198:201], v252 offset:0
	ds_read_b128 v[202:205], v253 offset:0
	ds_read_b128 v[206:209], v252 offset:2048
	ds_read_b128 v[210:213], v253 offset:2048
	ds_read_b128 v[214:217], v252 offset:4096
	ds_read_b128 v[218:221], v253 offset:4096
	s_waitcnt lgkmcnt(5)
	v_mfma_f32_16x16x32_bf16 v[68:71], v[198:201], v[124:127], 0
	s_waitcnt lgkmcnt(4)
	v_mfma_f32_16x16x32_bf16 v[68:71], v[202:205], v[128:131], v[68:71]
	ds_read_b128 v[198:201], v252 offset:6144
	ds_read_b128 v[202:205], v253 offset:6144
	s_waitcnt lgkmcnt(5)
	v_mfma_f32_16x16x32_bf16 v[72:75], v[206:209], v[124:127], 0
	s_waitcnt lgkmcnt(4)
	v_mfma_f32_16x16x32_bf16 v[72:75], v[210:213], v[128:131], v[72:75]
	ds_read_b128 v[206:209], v252 offset:8192
	ds_read_b128 v[210:213], v253 offset:8192
	s_waitcnt lgkmcnt(5)
	v_mfma_f32_16x16x32_bf16 v[76:79], v[214:217], v[124:127], 0
	s_waitcnt lgkmcnt(4)
	v_mfma_f32_16x16x32_bf16 v[76:79], v[218:221], v[128:131], v[76:79]
	ds_read_b128 v[214:217], v252 offset:10240
	ds_read_b128 v[218:221], v253 offset:10240
	s_waitcnt lgkmcnt(5)
	v_mfma_f32_16x16x32_bf16 v[80:83], v[198:201], v[124:127], 0
	s_waitcnt lgkmcnt(4)
	v_mfma_f32_16x16x32_bf16 v[80:83], v[202:205], v[128:131], v[80:83]
	ds_read_b128 v[198:201], v252 offset:12288
	ds_read_b128 v[202:205], v253 offset:12288
	s_waitcnt lgkmcnt(5)
	v_mfma_f32_16x16x32_bf16 v[84:87], v[206:209], v[124:127], 0
	s_waitcnt lgkmcnt(4)
	v_mfma_f32_16x16x32_bf16 v[84:87], v[210:213], v[128:131], v[84:87]
	ds_read_b128 v[206:209], v252 offset:14336
	ds_read_b128 v[210:213], v253 offset:14336
	s_waitcnt lgkmcnt(5)
	v_mfma_f32_16x16x32_bf16 v[88:91], v[214:217], v[124:127], 0
	s_waitcnt lgkmcnt(4)
	v_mfma_f32_16x16x32_bf16 v[88:91], v[218:221], v[128:131], v[88:91]
	ds_read_b128 v[214:217], v252 offset:16384
	ds_read_b128 v[218:221], v253 offset:16384
	s_waitcnt lgkmcnt(5)
	v_mfma_f32_16x16x32_bf16 v[92:95], v[198:201], v[124:127], 0
	s_waitcnt lgkmcnt(4)
	v_mfma_f32_16x16x32_bf16 v[92:95], v[202:205], v[128:131], v[92:95]
	ds_read_b128 v[198:201], v252 offset:18432
	ds_read_b128 v[202:205], v253 offset:18432
	v_cmp_lt_u32_e32 vcc, v139, v3
	s_waitcnt lgkmcnt(5)
	v_mfma_f32_16x16x32_bf16 v[96:99], v[206:209], v[124:127], 0
	s_waitcnt lgkmcnt(4)
	v_mfma_f32_16x16x32_bf16 v[96:99], v[210:213], v[128:131], v[96:99]
	ds_read_b128 v[206:209], v252 offset:20480
	ds_read_b128 v[210:213], v253 offset:20480
	v_cmp_lt_u32_e64 s[10:11], v156, v3
	s_waitcnt lgkmcnt(5)
	v_mfma_f32_16x16x32_bf16 v[100:103], v[214:217], v[124:127], 0
	s_waitcnt lgkmcnt(4)
	v_mfma_f32_16x16x32_bf16 v[100:103], v[218:221], v[128:131], v[100:103]
	ds_read_b128 v[214:217], v252 offset:22528
	ds_read_b128 v[218:221], v253 offset:22528
	v_cmp_lt_u32_e64 s[38:39], v157, v3
	v_cndmask_b32_e64 v68, v68, v239, vcc
	s_waitcnt lgkmcnt(5)
	v_mfma_f32_16x16x32_bf16 v[104:107], v[198:201], v[124:127], 0
	s_waitcnt lgkmcnt(4)
	v_mfma_f32_16x16x32_bf16 v[104:107], v[202:205], v[128:131], v[104:107]
	ds_read_b128 v[198:201], v252 offset:24576
	ds_read_b128 v[202:205], v253 offset:24576
	v_cmp_lt_u32_e32 vcc, v158, v3
	v_cndmask_b32_e64 v69, v69, v239, s[10:11]
	s_waitcnt lgkmcnt(5)
	v_mfma_f32_16x16x32_bf16 v[108:111], v[206:209], v[124:127], 0
	s_waitcnt lgkmcnt(4)
	v_mfma_f32_16x16x32_bf16 v[108:111], v[210:213], v[128:131], v[108:111]
	ds_read_b128 v[206:209], v252 offset:26624
	ds_read_b128 v[210:213], v253 offset:26624
	v_cmp_lt_u32_e64 s[10:11], v159, v3
	v_cndmask_b32_e64 v70, v70, v239, s[38:39]
	s_waitcnt lgkmcnt(5)
	v_mfma_f32_16x16x32_bf16 v[112:115], v[214:217], v[124:127], 0
	s_waitcnt lgkmcnt(4)
	v_mfma_f32_16x16x32_bf16 v[112:115], v[218:221], v[128:131], v[112:115]
	ds_read_b128 v[214:217], v252 offset:28672
	ds_read_b128 v[218:221], v253 offset:28672
	v_cmp_lt_u32_e64 s[38:39], v160, v3
	v_cndmask_b32_e64 v71, v71, v239, vcc
	s_waitcnt lgkmcnt(5)
	v_mfma_f32_16x16x32_bf16 v[116:119], v[198:201], v[124:127], 0
	s_waitcnt lgkmcnt(4)
	v_mfma_f32_16x16x32_bf16 v[116:119], v[202:205], v[128:131], v[116:119]
	ds_read_b128 v[198:201], v252 offset:30720
	ds_read_b128 v[202:205], v253 offset:30720
	v_cmp_lt_u32_e32 vcc, v161, v3
	v_cndmask_b32_e64 v72, v72, v239, s[10:11]
	s_waitcnt lgkmcnt(5)
	v_mfma_f32_16x16x32_bf16 v[120:123], v[206:209], v[124:127], 0
	s_waitcnt lgkmcnt(4)
	v_mfma_f32_16x16x32_bf16 v[120:123], v[210:213], v[128:131], v[120:123]
	ds_read_b128 v[206:209], v252 offset:32768
	ds_read_b128 v[210:213], v253 offset:32768
	v_cmp_lt_u32_e64 s[10:11], v162, v3
	v_cndmask_b32_e64 v73, v73, v239, s[38:39]
	s_waitcnt lgkmcnt(5)
	v_mfma_f32_16x16x32_bf16 v[182:185], v[214:217], v[124:127], 0
	s_waitcnt lgkmcnt(4)
	v_mfma_f32_16x16x32_bf16 v[182:185], v[218:221], v[128:131], v[182:185]
	ds_read_b128 v[214:217], v252 offset:34816
	ds_read_b128 v[218:221], v253 offset:34816
	s_waitcnt lgkmcnt(5)
	v_mfma_f32_16x16x32_bf16 v[186:189], v[198:201], v[124:127], 0
	s_waitcnt lgkmcnt(4)
	v_mfma_f32_16x16x32_bf16 v[186:189], v[202:205], v[128:131], v[186:189]
	s_waitcnt lgkmcnt(3)
	v_mfma_f32_16x16x32_bf16 v[190:193], v[206:209], v[124:127], 0
	s_waitcnt lgkmcnt(2)
	v_mfma_f32_16x16x32_bf16 v[190:193], v[210:213], v[128:131], v[190:193]
	s_waitcnt lgkmcnt(1)
	v_mfma_f32_16x16x32_bf16 v[194:197], v[214:217], v[124:127], 0
	s_waitcnt lgkmcnt(0)
	v_mfma_f32_16x16x32_bf16 v[194:197], v[218:221], v[128:131], v[194:197]
	v_add_u32_e32 v146, s37, v145
	v_add_u32_e32 v147, v146, v164
	v_cndmask_b32_e64 v74, v74, v239, vcc
	v_cndmask_b32_e64 v75, v75, v239, s[10:11]
	v_add_u32_e32 v146, v146, v163
	s_nop 3
	v_cmp_gt_u32_e32 vcc, v139, v3
	v_cmp_gt_u32_e64 s[10:11], v156, v3
	v_cmp_gt_u32_e64 s[38:39], v157, v3
	v_cndmask_b32_e64 v190, v190, v239, vcc
	v_cmp_gt_u32_e32 vcc, v158, v3
	v_cndmask_b32_e64 v191, v191, v239, s[10:11]
	v_cmp_gt_u32_e64 s[10:11], v159, v3
	v_cndmask_b32_e64 v192, v192, v239, s[38:39]
	v_cmp_gt_u32_e64 s[38:39], v160, v3
	v_cndmask_b32_e64 v193, v193, v239, vcc
	v_cmp_gt_u32_e32 vcc, v161, v3
	v_cndmask_b32_e64 v194, v194, v239, s[10:11]
	v_cmp_gt_u32_e64 s[10:11], v162, v3
	v_cndmask_b32_e64 v195, v195, v239, s[38:39]
	s_nop 0
	v_cndmask_b32_e64 v196, v196, v239, vcc
	v_cndmask_b32_e64 v197, v197, v239, s[10:11]
	s_andn2_b64 vcc, exec, s[94:95]
	s_cbranch_vccnz .Lwa_nomask
; __device__ __forceinline__ float shx(float v, int lane, int mask) { return __int_as_float(__builtin_amdgcn_ds_bpermute((lane ^ mask) << 2, __float_as_int(v))); }
; __device__ __forceinline__ float x32_max(float v) { auto rr = __builtin_amdgcn_permlane32_swap(__float_as_uint(v), __float_as_uint(v), false, false); return fmaxf(__uint_as_float(rr[0]), __uint_as_float(rr[1])); }
; __device__ __forceinline__ void mixer_unit(const Params& p, LAS unsigned char* lds, int tile, int layer, int wave_s) {
;     ...
;                 if (inv_lo || inv_hi) {
; #pragma unroll
;                     for (int c = 0; c < 9; ++c) {
;                         const int beta = beta0 + c;
;                         const bool cinv = (inv_lo && beta < 4) || (inv_hi && beta >= 8);
; #pragma unroll
;                         for (int w = 0; w < 2; ++w)
; #pragma unroll
;                             for (int r = 0; r < 4; ++r) S[c][w][r] = cinv ? -INFINITY : S[c][w][r];
;                     }
;                 }
;                 float mx = sink;
; #pragma unroll
;                 for (int c = 0; c < 9; ++c)
; #pragma unroll
;                     for (int w = 0; w < 2; ++w) { mx = __builtin_fmaxf(__builtin_fmaxf(mx, S[c][w][0]), S[c][w][1]); mx = __builtin_fmaxf(__builtin_fmaxf(mx, S[c][w][2]), S[c][w][3]); }
;                 mx = fmaxf(mx, shx(mx, lane, 16)); mx = x32_max(mx);
	s_add_i32 s10, s76, s73
	s_add_i32 s38, s10, -16
	v_cndmask_b32_e64 v68, v68, v239, s[8:9]
	v_cndmask_b32_e64 v69, v69, v239, s[8:9]
	v_cndmask_b32_e64 v70, v70, v239, s[8:9]
	v_cndmask_b32_e64 v71, v71, v239, s[8:9]
	v_cndmask_b32_e64 v72, v72, v239, s[8:9]
	v_cndmask_b32_e64 v73, v73, v239, s[8:9]
	v_cndmask_b32_e64 v74, v74, v239, s[8:9]
	v_cndmask_b32_e64 v75, v75, v239, s[8:9]
	v_cndmask_b32_e64 v190, v190, v239, s[4:5]
	v_cndmask_b32_e64 v191, v191, v239, s[4:5]
	v_cndmask_b32_e64 v192, v192, v239, s[4:5]
	v_cndmask_b32_e64 v193, v193, v239, s[4:5]
	v_cndmask_b32_e64 v194, v194, v239, s[4:5]
	v_cndmask_b32_e64 v195, v195, v239, s[4:5]
	v_cndmask_b32_e64 v196, v196, v239, s[4:5]
	v_cndmask_b32_e64 v197, v197, v239, s[4:5]
	s_cmpk_lt_u32 s38, 0x60
	s_cselect_b64 s[10:11], -1, 0
	s_and_b64 vcc, s[8:9], s[10:11]
	v_cndmask_b32_e64 v76, v76, v239, vcc
	v_cndmask_b32_e64 v77, v77, v239, vcc
	v_cndmask_b32_e64 v78, v78, v239, vcc
	v_cndmask_b32_e64 v79, v79, v239, vcc
	v_cndmask_b32_e64 v80, v80, v239, vcc
	v_cndmask_b32_e64 v81, v81, v239, vcc
	v_cndmask_b32_e64 v82, v82, v239, vcc
	v_cndmask_b32_e64 v83, v83, v239, vcc
	s_cmp_lt_u32 s38, 64
	s_cselect_b64 s[10:11], -1, 0
	s_and_b64 vcc, s[8:9], s[10:11]
	v_cndmask_b32_e64 v84, v84, v239, vcc
	v_cndmask_b32_e64 v85, v85, v239, vcc
	v_cndmask_b32_e64 v86, v86, v239, vcc
	v_cndmask_b32_e64 v87, v87, v239, vcc
	v_cndmask_b32_e64 v88, v88, v239, vcc
	v_cndmask_b32_e64 v89, v89, v239, vcc
	v_cndmask_b32_e64 v90, v90, v239, vcc
	v_cndmask_b32_e64 v91, v91, v239, vcc
	s_cmp_lt_u32 s38, 32
	s_cselect_b64 s[10:11], -1, 0
	s_and_b64 vcc, s[8:9], s[10:11]
	v_cndmask_b32_e64 v92, v92, v239, vcc
	v_cndmask_b32_e64 v93, v93, v239, vcc
	v_cndmask_b32_e64 v94, v94, v239, vcc
	v_cndmask_b32_e64 v95, v95, v239, vcc
	v_cndmask_b32_e64 v96, v96, v239, vcc
	v_cndmask_b32_e64 v97, v97, v239, vcc
	v_cndmask_b32_e64 v98, v98, v239, vcc
	v_cndmask_b32_e64 v99, v99, v239, vcc
	s_cmpk_gt_u32 s38, 0x5f
	s_cselect_b64 s[10:11], -1, 0
	s_and_b64 vcc, s[4:5], s[10:11]
	v_cndmask_b32_e64 v108, v108, v239, vcc
	v_cndmask_b32_e64 v109, v109, v239, vcc
	v_cndmask_b32_e64 v110, v110, v239, vcc
	v_cndmask_b32_e64 v111, v111, v239, vcc
	v_cndmask_b32_e64 v112, v112, v239, vcc
	v_cndmask_b32_e64 v113, v113, v239, vcc
	v_cndmask_b32_e64 v114, v114, v239, vcc
	v_cndmask_b32_e64 v115, v115, v239, vcc
	s_cmp_gt_u32 s38, 63
	s_cselect_b64 s[10:11], -1, 0
	s_and_b64 vcc, s[4:5], s[10:11]
	v_cndmask_b32_e64 v116, v116, v239, vcc
	v_cndmask_b32_e64 v117, v117, v239, vcc
	v_cndmask_b32_e64 v118, v118, v239, vcc
	v_cndmask_b32_e64 v119, v119, v239, vcc
	v_cndmask_b32_e64 v120, v120, v239, vcc
	v_cndmask_b32_e64 v121, v121, v239, vcc
	v_cndmask_b32_e64 v122, v122, v239, vcc
	v_cndmask_b32_e64 v123, v123, v239, vcc
	s_cmp_gt_u32 s38, 31
	s_cselect_b64 s[10:11], -1, 0
	s_and_b64 vcc, s[4:5], s[10:11]
	v_cndmask_b32_e64 v182, v182, v239, vcc
	v_cndmask_b32_e64 v183, v183, v239, vcc
	v_cndmask_b32_e64 v184, v184, v239, vcc
	v_cndmask_b32_e64 v185, v185, v239, vcc
	v_cndmask_b32_e64 v186, v186, v239, vcc
	v_cndmask_b32_e64 v187, v187, v239, vcc
	v_cndmask_b32_e64 v188, v188, v239, vcc
	v_cndmask_b32_e64 v189, v189, v239, vcc
.Lwa_nomask:
	v_max3_f32 v234, v1, v68, v72
	v_max_f32_e32 v235, v69, v73
	v_max_f32_e32 v2, v70, v74
	v_max_f32_e32 v3, v71, v75
	v_max3_f32 v234, v234, v76, v80
	v_max3_f32 v235, v235, v77, v81
	v_max3_f32 v2, v2, v78, v82
	v_max3_f32 v3, v3, v79, v83
	v_max3_f32 v234, v234, v84, v88
	v_max3_f32 v235, v235, v85, v89
	v_max3_f32 v2, v2, v86, v90
	v_max3_f32 v3, v3, v87, v91
	v_max3_f32 v234, v234, v92, v96
	v_max3_f32 v235, v235, v93, v97
	v_max3_f32 v2, v2, v94, v98
	v_max3_f32 v3, v3, v95, v99
	v_max3_f32 v234, v234, v100, v104
	v_max3_f32 v235, v235, v101, v105
	v_max3_f32 v2, v2, v102, v106
	v_max3_f32 v3, v3, v103, v107
	v_max3_f32 v234, v234, v108, v112
	v_max3_f32 v235, v235, v109, v113
	v_max3_f32 v2, v2, v110, v114
	v_max3_f32 v3, v3, v111, v115
	v_max3_f32 v234, v234, v116, v120
	v_max3_f32 v235, v235, v117, v121
	v_max3_f32 v2, v2, v118, v122
	v_max3_f32 v3, v3, v119, v123
	v_max3_f32 v234, v234, v182, v186
	v_max3_f32 v235, v235, v183, v187
	v_max3_f32 v2, v2, v184, v188
	v_max3_f32 v3, v3, v185, v189
	v_max3_f32 v234, v234, v190, v194
	v_max3_f32 v235, v235, v191, v195
	v_max3_f32 v2, v2, v192, v196
	v_max3_f32 v3, v3, v193, v197
	v_max3_f32 v234, v234, v235, v2
	v_max_f32_e32 v234, v234, v3
	ds_bpermute_b32 v235, v144, v234
	v_mov_b32_e32 v248, s36
	v_mov_b32_e32 v249, s36
	v_mov_b32_e32 v250, s36
	v_mov_b32_e32 v251, s36
	v_add_u32_e32 v252, 0xc000, v146
	v_add_u32_e32 v253, 0xc000, v147
	s_waitcnt lgkmcnt(0)
; #define LAS __attribute__((address_space(3)))
; __device__ __forceinline__ unsigned cvt_pk_bf16(float lo, float hi) { unsigned r; asm volatile("v_cvt_pk_bf16_f32 %0, %1, %2" : "=v"(r) : "v"(lo), "v"(hi)); return r; }
; __device__ __forceinline__ float shx(float v, int lane, int mask) { return __int_as_float(__builtin_amdgcn_ds_bpermute((lane ^ mask) << 2, __float_as_int(v))); }
; __device__ __forceinline__ float x32_max(float v) { auto rr = __builtin_amdgcn_permlane32_swap(__float_as_uint(v), __float_as_uint(v), false, false); return fmaxf(__uint_as_float(rr[0]), __uint_as_float(rr[1])); }
; __device__ __forceinline__ void mixer_unit(const Params& p, LAS unsigned char* lds, int tile, int layer, int wave_s) {
;     ...
;                 mx = fmaxf(mx, shx(mx, lane, 16)); mx = x32_max(mx);
;                 const float mb = mx * LOG2E;
; #pragma unroll
;                 for (int c = 0; c < 9; ++c)
; #pragma unroll
;                     for (int w = 0; w < 2; ++w)
; #pragma unroll
;                         for (int r = 0; r < 4; ++r) S[c][w][r] = __builtin_amdgcn_exp2f(S[c][w][r] * LOG2E - mb);
;                 f32x4 OS = (f32x4){0.f, 0.f, 0.f, 0.f};
;                 f32x4 O[4];
;                 LAS unsigned char* vbd[4];
; #pragma unroll
;                 for (int dt = 0; dt < 4; ++dt) { O[dt] = (f32x4){0.f, 0.f, 0.f, 0.f}; vbd[dt] = lds + L_VT + vlane + beta0 * 4096 + ((((4 * (dt >> 1) + (rho & 3)) ^ fv) << 4) + 8 * (dt & 1)); }
; #pragma unroll
;                 for (int c = 0; c < 9; ++c) {
;                     const int beta = beta0 + c;
;                     u32x4 pw; pw.x = cvt_pk_bf16(S[c][0][0], S[c][0][1]); pw.y = cvt_pk_bf16(S[c][0][2], S[c][0][3]); pw.z = cvt_pk_bf16(S[c][1][0], S[c][1][1]); pw.w = cvt_pk_bf16(S[c][1][2], S[c][1][3]);
	v_max_f32_e32 v234, v234, v235
	v_mov_b32_e32 v235, v234
	s_nop 1
	v_permlane32_swap_b32_e32 v234, v235
	v_max_f32_e32 v234, v234, v235
	v_mul_f32_e32 v2, s80, v234
	ds_read_b64_tr_b16 v[198:199], v146 offset:49152
	ds_read_b64_tr_b16 v[200:201], v146 offset:49664
	ds_read_b64_tr_b16 v[202:203], v146 offset:49160
	ds_read_b64_tr_b16 v[204:205], v146 offset:49672
	ds_read_b64_tr_b16 v[206:207], v147 offset:49152
	ds_read_b64_tr_b16 v[208:209], v147 offset:49664
	ds_read_b64_tr_b16 v[210:211], v147 offset:49160
	ds_read_b64_tr_b16 v[212:213], v147 offset:49672
	v_fma_f32 v68, v68, s80, -v2
	v_fma_f32 v69, v69, s80, -v2
	v_fma_f32 v70, v70, s80, -v2
	v_fma_f32 v71, v71, s80, -v2
	v_exp_f32_e32 v68, v68
	v_exp_f32_e32 v69, v69
	v_exp_f32_e32 v70, v70
	v_exp_f32_e32 v71, v71
	v_fma_f32 v72, v72, s80, -v2
	v_fma_f32 v73, v73, s80, -v2
	v_fma_f32 v74, v74, s80, -v2
	v_fma_f32 v75, v75, s80, -v2
	v_exp_f32_e32 v72, v72
	v_exp_f32_e32 v73, v73
	v_exp_f32_e32 v74, v74
	v_exp_f32_e32 v75, v75
	v_fma_f32 v76, v76, s80, -v2
	v_fma_f32 v77, v77, s80, -v2
	v_fma_f32 v78, v78, s80, -v2
	v_fma_f32 v79, v79, s80, -v2
	v_exp_f32_e32 v76, v76
	v_exp_f32_e32 v77, v77
	v_exp_f32_e32 v78, v78
	v_exp_f32_e32 v79, v79
	v_fma_f32 v80, v80, s80, -v2
	v_fma_f32 v81, v81, s80, -v2
	v_fma_f32 v82, v82, s80, -v2
	v_fma_f32 v83, v83, s80, -v2
	v_exp_f32_e32 v80, v80
	v_exp_f32_e32 v81, v81
	v_exp_f32_e32 v82, v82
	v_exp_f32_e32 v83, v83
	v_fma_f32 v84, v84, s80, -v2
	v_fma_f32 v85, v85, s80, -v2
	v_fma_f32 v86, v86, s80, -v2
	v_fma_f32 v87, v87, s80, -v2
	v_exp_f32_e32 v84, v84
	v_exp_f32_e32 v85, v85
	v_exp_f32_e32 v86, v86
	v_exp_f32_e32 v87, v87
	v_fma_f32 v88, v88, s80, -v2
	v_fma_f32 v89, v89, s80, -v2
	v_fma_f32 v90, v90, s80, -v2
	v_fma_f32 v91, v91, s80, -v2
	v_exp_f32_e32 v88, v88
	v_exp_f32_e32 v89, v89
	v_exp_f32_e32 v90, v90
	v_exp_f32_e32 v91, v91
	v_fma_f32 v92, v92, s80, -v2
	v_fma_f32 v93, v93, s80, -v2
	v_fma_f32 v94, v94, s80, -v2
	v_fma_f32 v95, v95, s80, -v2
	v_exp_f32_e32 v92, v92
	v_exp_f32_e32 v93, v93
	v_exp_f32_e32 v94, v94
	v_exp_f32_e32 v95, v95
	v_fma_f32 v96, v96, s80, -v2
	v_fma_f32 v97, v97, s80, -v2
	v_fma_f32 v98, v98, s80, -v2
	v_fma_f32 v99, v99, s80, -v2
	v_exp_f32_e32 v96, v96
	v_exp_f32_e32 v97, v97
	v_exp_f32_e32 v98, v98
	v_exp_f32_e32 v99, v99
	v_fma_f32 v100, v100, s80, -v2
	v_fma_f32 v101, v101, s80, -v2
	v_fma_f32 v102, v102, s80, -v2
	v_fma_f32 v103, v103, s80, -v2
	v_exp_f32_e32 v100, v100
	v_exp_f32_e32 v101, v101
	v_exp_f32_e32 v102, v102
	v_exp_f32_e32 v103, v103
	v_fma_f32 v104, v104, s80, -v2
	v_fma_f32 v105, v105, s80, -v2
	v_fma_f32 v106, v106, s80, -v2
	v_fma_f32 v107, v107, s80, -v2
	v_exp_f32_e32 v104, v104
	v_exp_f32_e32 v105, v105
	v_exp_f32_e32 v106, v106
	v_exp_f32_e32 v107, v107
	v_fma_f32 v108, v108, s80, -v2
	v_fma_f32 v109, v109, s80, -v2
	v_fma_f32 v110, v110, s80, -v2
	v_fma_f32 v111, v111, s80, -v2
	v_exp_f32_e32 v108, v108
	v_exp_f32_e32 v109, v109
	v_exp_f32_e32 v110, v110
	v_exp_f32_e32 v111, v111
	v_fma_f32 v112, v112, s80, -v2
	v_fma_f32 v113, v113, s80, -v2
	v_fma_f32 v114, v114, s80, -v2
	v_fma_f32 v115, v115, s80, -v2
	v_exp_f32_e32 v112, v112
	v_exp_f32_e32 v113, v113
	v_exp_f32_e32 v114, v114
	v_exp_f32_e32 v115, v115
	v_fma_f32 v116, v116, s80, -v2
	v_fma_f32 v117, v117, s80, -v2
	v_fma_f32 v118, v118, s80, -v2
	v_fma_f32 v119, v119, s80, -v2
	v_exp_f32_e32 v116, v116
	v_exp_f32_e32 v117, v117
	v_exp_f32_e32 v118, v118
	v_exp_f32_e32 v119, v119
	v_fma_f32 v120, v120, s80, -v2
	v_fma_f32 v121, v121, s80, -v2
	v_fma_f32 v122, v122, s80, -v2
	v_fma_f32 v123, v123, s80, -v2
	v_exp_f32_e32 v120, v120
	v_exp_f32_e32 v121, v121
	v_exp_f32_e32 v122, v122
	v_exp_f32_e32 v123, v123
	v_fma_f32 v182, v182, s80, -v2
	v_fma_f32 v183, v183, s80, -v2
	v_fma_f32 v184, v184, s80, -v2
	v_fma_f32 v185, v185, s80, -v2
	v_exp_f32_e32 v182, v182
	v_exp_f32_e32 v183, v183
	v_exp_f32_e32 v184, v184
	v_exp_f32_e32 v185, v185
	v_fma_f32 v186, v186, s80, -v2
	v_fma_f32 v187, v187, s80, -v2
	v_fma_f32 v188, v188, s80, -v2
	v_fma_f32 v189, v189, s80, -v2
	v_exp_f32_e32 v186, v186
	v_exp_f32_e32 v187, v187
	v_exp_f32_e32 v188, v188
	v_exp_f32_e32 v189, v189
	v_fma_f32 v190, v190, s80, -v2
	v_fma_f32 v191, v191, s80, -v2
	v_fma_f32 v192, v192, s80, -v2
	v_fma_f32 v193, v193, s80, -v2
	v_exp_f32_e32 v190, v190
	v_exp_f32_e32 v191, v191
	v_exp_f32_e32 v192, v192
	v_exp_f32_e32 v193, v193
	v_fma_f32 v194, v194, s80, -v2
	v_fma_f32 v195, v195, s80, -v2
	v_fma_f32 v196, v196, s80, -v2
	v_fma_f32 v197, v197, s80, -v2
	v_exp_f32_e32 v194, v194
	v_exp_f32_e32 v195, v195
	v_exp_f32_e32 v196, v196
	v_exp_f32_e32 v197, v197
	v_sub_f32_e32 v234, v181, v2
	v_exp_f32_e32 v234, v234
	v_cvt_pk_bf16_f32 v68, v68, v69
	v_cvt_pk_bf16_f32 v69, v70, v71
	v_cvt_pk_bf16_f32 v70, v72, v73
	v_cvt_pk_bf16_f32 v71, v74, v75
	v_cvt_pk_bf16_f32 v76, v76, v77
	v_cvt_pk_bf16_f32 v77, v78, v79
	v_cvt_pk_bf16_f32 v78, v80, v81
	v_cvt_pk_bf16_f32 v79, v82, v83
	ds_read_b64_tr_b16 v[72:73], v146 offset:53248
	ds_read_b64_tr_b16 v[74:75], v146 offset:53760
	ds_read_b64_tr_b16 v[80:81], v146 offset:53256
	ds_read_b64_tr_b16 v[82:83], v146 offset:53768
	ds_read_b64_tr_b16 v[214:215], v147 offset:53248
	ds_read_b64_tr_b16 v[216:217], v147 offset:53760
	ds_read_b64_tr_b16 v[218:219], v147 offset:53256
	ds_read_b64_tr_b16 v[220:221], v147 offset:53768
	s_waitcnt lgkmcnt(8)
; __device__ __forceinline__ unsigned cvt_pk_bf16(float lo, float hi) { unsigned r; asm volatile("v_cvt_pk_bf16_f32 %0, %1, %2" : "=v"(r) : "v"(lo), "v"(hi)); return r; }
; __device__ __forceinline__ v4i16_t tr16(LAS unsigned char* a) { return __builtin_amdgcn_ds_read_tr16_b64_v4i16((LAS v4i16_t*)a); }
; __device__ __forceinline__ void mixer_unit(const Params& p, LAS unsigned char* lds, int tile, int layer, int wave_s) {
;     ...
; #pragma unroll
;                 for (int c = 0; c < 9; ++c) {
;                     const int beta = beta0 + c;
;                     u32x4 pw; pw.x = cvt_pk_bf16(S[c][0][0], S[c][0][1]); pw.y = cvt_pk_bf16(S[c][0][2], S[c][0][3]); pw.z = cvt_pk_bf16(S[c][1][0], S[c][1][1]); pw.w = cvt_pk_bf16(S[c][1][2], S[c][1][3]);
;                     const bf16x8 pf = __builtin_bit_cast(bf16x8, pw);
;                     OS = __builtin_amdgcn_mfma_f32_16x16x32_bf16(ONES8, pf, OS, 0, 0, 0);
; #pragma unroll
;                     for (int dt = 0; dt < 4; ++dt) {
;                         const v4i16_t lo = tr16(vbd[dt] + c * 4096), hi = tr16(vbd[dt] + c * 4096 + 512);
;                         const bf16x8 vf = (bf16x8){lo[0], lo[1], lo[2], lo[3], hi[0], hi[1], hi[2], hi[3]};
;                         O[dt] = __builtin_amdgcn_mfma_f32_16x16x32_bf16(vf, pf, O[dt], 0, 0, 0);
;                     }
;                 }
	v_mfma_f32_16x16x32_bf16 v[244:247], v[248:251], v[68:71], 0
	v_cvt_pk_bf16_f32 v84, v84, v85
	v_cvt_pk_bf16_f32 v85, v86, v87
	v_cvt_pk_bf16_f32 v86, v88, v89
	v_cvt_pk_bf16_f32 v87, v90, v91
	v_mfma_f32_16x16x32_bf16 v[222:225], v[198:201], v[68:71], 0
	v_mfma_f32_16x16x32_bf16 v[226:229], v[202:205], v[68:71], 0
	v_mfma_f32_16x16x32_bf16 v[230:233], v[206:209], v[68:71], 0
	v_mfma_f32_16x16x32_bf16 v[240:243], v[210:213], v[68:71], 0
	ds_read_b64_tr_b16 v[198:199], v146 offset:57344
	ds_read_b64_tr_b16 v[200:201], v146 offset:57856
	ds_read_b64_tr_b16 v[202:203], v146 offset:57352
	ds_read_b64_tr_b16 v[204:205], v146 offset:57864
	ds_read_b64_tr_b16 v[206:207], v147 offset:57344
	ds_read_b64_tr_b16 v[208:209], v147 offset:57856
	ds_read_b64_tr_b16 v[210:211], v147 offset:57352
	ds_read_b64_tr_b16 v[212:213], v147 offset:57864
	s_waitcnt lgkmcnt(8)
	v_mfma_f32_16x16x32_bf16 v[244:247], v[248:251], v[76:79], v[244:247]
	v_cvt_pk_bf16_f32 v92, v92, v93
	v_cvt_pk_bf16_f32 v93, v94, v95
	v_cvt_pk_bf16_f32 v94, v96, v97
	v_cvt_pk_bf16_f32 v95, v98, v99
	v_mfma_f32_16x16x32_bf16 v[222:225], v[72:75], v[76:79], v[222:225]
	v_mfma_f32_16x16x32_bf16 v[226:229], v[80:83], v[76:79], v[226:229]
	v_mfma_f32_16x16x32_bf16 v[230:233], v[214:217], v[76:79], v[230:233]
	v_mfma_f32_16x16x32_bf16 v[240:243], v[218:221], v[76:79], v[240:243]
	ds_read_b64_tr_b16 v[72:73], v146 offset:61440
	ds_read_b64_tr_b16 v[74:75], v146 offset:61952
	ds_read_b64_tr_b16 v[80:81], v146 offset:61448
	ds_read_b64_tr_b16 v[82:83], v146 offset:61960
	ds_read_b64_tr_b16 v[214:215], v147 offset:61440
	ds_read_b64_tr_b16 v[216:217], v147 offset:61952
	ds_read_b64_tr_b16 v[218:219], v147 offset:61448
	ds_read_b64_tr_b16 v[220:221], v147 offset:61960
	s_waitcnt lgkmcnt(8)
	v_mfma_f32_16x16x32_bf16 v[244:247], v[248:251], v[84:87], v[244:247]
	v_cvt_pk_bf16_f32 v100, v100, v101
	v_cvt_pk_bf16_f32 v101, v102, v103
	v_cvt_pk_bf16_f32 v102, v104, v105
	v_cvt_pk_bf16_f32 v103, v106, v107
	v_mfma_f32_16x16x32_bf16 v[222:225], v[198:201], v[84:87], v[222:225]
	v_mfma_f32_16x16x32_bf16 v[226:229], v[202:205], v[84:87], v[226:229]
	v_mfma_f32_16x16x32_bf16 v[230:233], v[206:209], v[84:87], v[230:233]
	v_mfma_f32_16x16x32_bf16 v[240:243], v[210:213], v[84:87], v[240:243]
	ds_read_b64_tr_b16 v[198:199], v252 offset:16384
	ds_read_b64_tr_b16 v[200:201], v252 offset:16896
	ds_read_b64_tr_b16 v[202:203], v252 offset:16392
	ds_read_b64_tr_b16 v[204:205], v252 offset:16904
	ds_read_b64_tr_b16 v[206:207], v253 offset:16384
	ds_read_b64_tr_b16 v[208:209], v253 offset:16896
	ds_read_b64_tr_b16 v[210:211], v253 offset:16392
	ds_read_b64_tr_b16 v[212:213], v253 offset:16904
	s_waitcnt lgkmcnt(8)
	v_mfma_f32_16x16x32_bf16 v[244:247], v[248:251], v[92:95], v[244:247]
	v_cvt_pk_bf16_f32 v108, v108, v109
	v_cvt_pk_bf16_f32 v109, v110, v111
	v_cvt_pk_bf16_f32 v110, v112, v113
	v_cvt_pk_bf16_f32 v111, v114, v115
	v_mfma_f32_16x16x32_bf16 v[222:225], v[72:75], v[92:95], v[222:225]
	v_mfma_f32_16x16x32_bf16 v[226:229], v[80:83], v[92:95], v[226:229]
	v_mfma_f32_16x16x32_bf16 v[230:233], v[214:217], v[92:95], v[230:233]
	v_mfma_f32_16x16x32_bf16 v[240:243], v[218:221], v[92:95], v[240:243]
	ds_read_b64_tr_b16 v[72:73], v252 offset:20480
	ds_read_b64_tr_b16 v[74:75], v252 offset:20992
	ds_read_b64_tr_b16 v[80:81], v252 offset:20488
	ds_read_b64_tr_b16 v[82:83], v252 offset:21000
	ds_read_b64_tr_b16 v[214:215], v253 offset:20480
	ds_read_b64_tr_b16 v[216:217], v253 offset:20992
	ds_read_b64_tr_b16 v[218:219], v253 offset:20488
	ds_read_b64_tr_b16 v[220:221], v253 offset:21000
	s_waitcnt lgkmcnt(8)
	v_mfma_f32_16x16x32_bf16 v[244:247], v[248:251], v[100:103], v[244:247]
	v_cvt_pk_bf16_f32 v116, v116, v117
	v_cvt_pk_bf16_f32 v117, v118, v119
	v_cvt_pk_bf16_f32 v118, v120, v121
	v_cvt_pk_bf16_f32 v119, v122, v123
	v_mfma_f32_16x16x32_bf16 v[222:225], v[198:201], v[100:103], v[222:225]
	v_mfma_f32_16x16x32_bf16 v[226:229], v[202:205], v[100:103], v[226:229]
	v_mfma_f32_16x16x32_bf16 v[230:233], v[206:209], v[100:103], v[230:233]
	v_mfma_f32_16x16x32_bf16 v[240:243], v[210:213], v[100:103], v[240:243]
	ds_read_b64_tr_b16 v[198:199], v252 offset:24576
	ds_read_b64_tr_b16 v[200:201], v252 offset:25088
	ds_read_b64_tr_b16 v[202:203], v252 offset:24584
	ds_read_b64_tr_b16 v[204:205], v252 offset:25096
	ds_read_b64_tr_b16 v[206:207], v253 offset:24576
	ds_read_b64_tr_b16 v[208:209], v253 offset:25088
	ds_read_b64_tr_b16 v[210:211], v253 offset:24584
	ds_read_b64_tr_b16 v[212:213], v253 offset:25096
	s_waitcnt lgkmcnt(8)
	v_mfma_f32_16x16x32_bf16 v[244:247], v[248:251], v[108:111], v[244:247]
	v_cvt_pk_bf16_f32 v182, v182, v183
	v_cvt_pk_bf16_f32 v183, v184, v185
	v_cvt_pk_bf16_f32 v184, v186, v187
	v_cvt_pk_bf16_f32 v185, v188, v189
	v_mfma_f32_16x16x32_bf16 v[222:225], v[72:75], v[108:111], v[222:225]
	v_mfma_f32_16x16x32_bf16 v[226:229], v[80:83], v[108:111], v[226:229]
	v_mfma_f32_16x16x32_bf16 v[230:233], v[214:217], v[108:111], v[230:233]
	v_mfma_f32_16x16x32_bf16 v[240:243], v[218:221], v[108:111], v[240:243]
	ds_read_b64_tr_b16 v[72:73], v252 offset:28672
	ds_read_b64_tr_b16 v[74:75], v252 offset:29184
	ds_read_b64_tr_b16 v[80:81], v252 offset:28680
	ds_read_b64_tr_b16 v[82:83], v252 offset:29192
	ds_read_b64_tr_b16 v[214:215], v253 offset:28672
	ds_read_b64_tr_b16 v[216:217], v253 offset:29184
	ds_read_b64_tr_b16 v[218:219], v253 offset:28680
	ds_read_b64_tr_b16 v[220:221], v253 offset:29192
	s_waitcnt lgkmcnt(8)
; __device__ __forceinline__ unsigned cvt_pk_bf16(float lo, float hi) { unsigned r; asm volatile("v_cvt_pk_bf16_f32 %0, %1, %2" : "=v"(r) : "v"(lo), "v"(hi)); return r; }
; __device__ __forceinline__ float bf_lo(unsigned w) { return __uint_as_float(w << 16); }
; __device__ __forceinline__ float bf_hi(unsigned w) { return __uint_as_float(w & 0xffff0000u); }
; __device__ __forceinline__ float shx(float v, int lane, int mask) { return __int_as_float(__builtin_amdgcn_ds_bpermute((lane ^ mask) << 2, __float_as_int(v))); }
; __device__ __forceinline__ float x32_sum(float v) { auto rr = __builtin_amdgcn_permlane32_swap(__float_as_uint(v), __float_as_uint(v), false, false); return __uint_as_float(rr[0]) + __uint_as_float(rr[1]); }
; __device__ __forceinline__ float silu_f(float x) { return x * __builtin_amdgcn_rcpf(1.0f + __builtin_amdgcn_exp2f(-x * LOG2E)); }
; __device__ __forceinline__ void mixer_unit(const Params& p, LAS unsigned char* lds, int tile, int layer, int wave_s) {
;     ...
;                         O[dt] = __builtin_amdgcn_mfma_f32_16x16x32_bf16(vf, pf, O[dt], 0, 0, 0);
;                     }
;                 }
;                 const float il = __builtin_amdgcn_rcpf(OS[0] + __builtin_amdgcn_exp2f(sink * LOG2E - mb));
;                 float ssq = 0.f;
; #pragma unroll
;                 for (int j = 0; j < 2; ++j) {
;                     const f32x4 o0 = O[2 * j] * il, o1 = O[2 * j + 1] * il;
;                     ssq += (o0[0] * o0[0] + o0[1] * o0[1]) + (o0[2] * o0[2] + o0[3] * o0[3]) + (o1[0] * o1[0] + o1[1] * o1[1]) + (o1[2] * o1[2] + o1[3] * o1[3]);
;                     u32x4 w;
;                     w.x = cvt_pk_bf16(o0[0] * silu_f(bf_lo(gt[j].x)), o0[1] * silu_f(bf_hi(gt[j].x)));
;                     w.y = cvt_pk_bf16(o0[2] * silu_f(bf_lo(gt[j].y)), o0[3] * silu_f(bf_hi(gt[j].y)));
;                     w.z = cvt_pk_bf16(o1[0] * silu_f(bf_lo(gt[j].z)), o1[1] * silu_f(bf_hi(gt[j].z)));
;                     w.w = cvt_pk_bf16(o1[2] * silu_f(bf_lo(gt[j].w)), o1[3] * silu_f(bf_hi(gt[j].w)));
;                     PG(u32x4, P, prow + C_Q + 32 * j) = w;
;                 }
;                 ssq += shx(ssq, lane, 16); ssq = x32_sum(ssq);
;                 if (g == 0) SSQ[hq * 128 + a + rho] = ssq;
	v_mfma_f32_16x16x32_bf16 v[244:247], v[248:251], v[116:119], v[244:247]
	v_cvt_pk_bf16_f32 v190, v190, v191
	v_cvt_pk_bf16_f32 v191, v192, v193
	v_cvt_pk_bf16_f32 v192, v194, v195
	v_cvt_pk_bf16_f32 v193, v196, v197
	v_mfma_f32_16x16x32_bf16 v[222:225], v[198:201], v[116:119], v[222:225]
	v_mfma_f32_16x16x32_bf16 v[226:229], v[202:205], v[116:119], v[226:229]
	v_mfma_f32_16x16x32_bf16 v[230:233], v[206:209], v[116:119], v[230:233]
	v_mfma_f32_16x16x32_bf16 v[240:243], v[210:213], v[116:119], v[240:243]
	ds_read_b64_tr_b16 v[198:199], v252 offset:32768
	ds_read_b64_tr_b16 v[200:201], v252 offset:33280
	ds_read_b64_tr_b16 v[202:203], v252 offset:32776
	ds_read_b64_tr_b16 v[204:205], v252 offset:33288
	ds_read_b64_tr_b16 v[206:207], v253 offset:32768
	ds_read_b64_tr_b16 v[208:209], v253 offset:33280
	ds_read_b64_tr_b16 v[210:211], v253 offset:32776
	ds_read_b64_tr_b16 v[212:213], v253 offset:33288
	s_waitcnt lgkmcnt(8)
	v_mfma_f32_16x16x32_bf16 v[244:247], v[248:251], v[182:185], v[244:247]
	v_mfma_f32_16x16x32_bf16 v[222:225], v[72:75], v[182:185], v[222:225]
	v_mfma_f32_16x16x32_bf16 v[226:229], v[80:83], v[182:185], v[226:229]
	v_mfma_f32_16x16x32_bf16 v[230:233], v[214:217], v[182:185], v[230:233]
	v_mfma_f32_16x16x32_bf16 v[240:243], v[218:221], v[182:185], v[240:243]
	s_waitcnt lgkmcnt(0)
	v_mfma_f32_16x16x32_bf16 v[244:247], v[248:251], v[190:193], v[244:247]
	v_mfma_f32_16x16x32_bf16 v[222:225], v[198:201], v[190:193], v[222:225]
	v_mfma_f32_16x16x32_bf16 v[226:229], v[202:205], v[190:193], v[226:229]
	v_mfma_f32_16x16x32_bf16 v[230:233], v[206:209], v[190:193], v[230:233]
	v_mfma_f32_16x16x32_bf16 v[240:243], v[210:213], v[190:193], v[240:243]
	s_waitcnt vmcnt(3)
	v_lshlrev_b32_e32 v68, 16, v64
	v_and_b32_e32 v69, 0xffff0000, v64
	v_lshlrev_b32_e32 v70, 16, v65
	v_and_b32_e32 v71, 0xffff0000, v65
	v_lshlrev_b32_e32 v72, 16, v66
	v_and_b32_e32 v73, 0xffff0000, v66
	v_lshlrev_b32_e32 v74, 16, v67
	v_and_b32_e32 v75, 0xffff0000, v67
	v_mul_f32_e32 v76, 0xbfb8aa3b, v68
	v_mul_f32_e32 v77, 0xbfb8aa3b, v69
	v_mul_f32_e32 v78, 0xbfb8aa3b, v70
	v_mul_f32_e32 v79, 0xbfb8aa3b, v71
	v_mul_f32_e32 v80, 0xbfb8aa3b, v72
	v_mul_f32_e32 v81, 0xbfb8aa3b, v73
	v_mul_f32_e32 v82, 0xbfb8aa3b, v74
	v_mul_f32_e32 v83, 0xbfb8aa3b, v75
	v_exp_f32_e32 v76, v76
	v_exp_f32_e32 v77, v77
	v_exp_f32_e32 v78, v78
	v_exp_f32_e32 v79, v79
	v_exp_f32_e32 v80, v80
	v_exp_f32_e32 v81, v81
	v_exp_f32_e32 v82, v82
	v_exp_f32_e32 v83, v83
	v_add_f32_e32 v76, 1.0, v76
	v_add_f32_e32 v77, 1.0, v77
	v_add_f32_e32 v78, 1.0, v78
	v_add_f32_e32 v79, 1.0, v79
	v_add_f32_e32 v80, 1.0, v80
	v_add_f32_e32 v81, 1.0, v81
	v_add_f32_e32 v82, 1.0, v82
	v_add_f32_e32 v83, 1.0, v83
	v_rcp_f32_e32 v76, v76
	v_rcp_f32_e32 v77, v77
	v_rcp_f32_e32 v78, v78
	v_rcp_f32_e32 v79, v79
	v_rcp_f32_e32 v80, v80
	v_rcp_f32_e32 v81, v81
	v_rcp_f32_e32 v82, v82
	v_rcp_f32_e32 v83, v83
	v_mul_f32_e32 v68, v76, v68
	v_mul_f32_e32 v69, v77, v69
	v_mul_f32_e32 v70, v78, v70
	v_mul_f32_e32 v71, v79, v71
	v_mul_f32_e32 v72, v80, v72
	v_mul_f32_e32 v73, v81, v73
	v_mul_f32_e32 v74, v82, v74
	v_mul_f32_e32 v75, v83, v75
	v_add_f32_e32 v235, v234, v244
	v_rcp_f32_e32 v235, v235
	s_nop 0
	v_mul_f32_e32 v222, v222, v235
	v_mul_f32_e32 v223, v223, v235
	v_mul_f32_e32 v224, v224, v235
	v_mul_f32_e32 v225, v225, v235
	v_mul_f32_e32 v226, v226, v235
	v_mul_f32_e32 v227, v227, v235
	v_mul_f32_e32 v228, v228, v235
	v_mul_f32_e32 v229, v229, v235
	v_mul_f32_e32 v252, v223, v223
	v_mul_f32_e32 v253, v225, v225
	v_fmac_f32_e32 v252, v222, v222
	v_fmac_f32_e32 v253, v224, v224
	v_add_f32_e32 v250, v252, v253
	v_mul_f32_e32 v253, v227, v227
	v_fmac_f32_e32 v253, v226, v226
	v_mul_f32_e32 v252, v229, v229
	v_add_f32_e32 v250, v253, v250
	v_fmac_f32_e32 v252, v228, v228
	v_add_f32_e32 v250, v252, v250
	v_mul_f32_e32 v68, v68, v222
	v_mul_f32_e32 v69, v69, v223
	v_mul_f32_e32 v70, v70, v224
	v_mul_f32_e32 v71, v71, v225
	v_mul_f32_e32 v72, v72, v226
	v_mul_f32_e32 v73, v73, v227
	v_mul_f32_e32 v74, v74, v228
	v_mul_f32_e32 v75, v75, v229
	v_cvt_pk_bf16_f32 v64, v68, v69
	v_cvt_pk_bf16_f32 v65, v70, v71
	v_cvt_pk_bf16_f32 v66, v72, v73
	v_cvt_pk_bf16_f32 v67, v74, v75
	global_store_dwordx4 v180, v[64:67], s[16:17]
	s_waitcnt vmcnt(3)
	v_lshlrev_b32_e32 v84, 16, v60
	v_and_b32_e32 v85, 0xffff0000, v60
	v_lshlrev_b32_e32 v86, 16, v61
	v_and_b32_e32 v87, 0xffff0000, v61
	v_lshlrev_b32_e32 v88, 16, v62
	v_and_b32_e32 v89, 0xffff0000, v62
	v_lshlrev_b32_e32 v90, 16, v63
	v_and_b32_e32 v91, 0xffff0000, v63
	v_mul_f32_e32 v92, 0xbfb8aa3b, v84
	v_mul_f32_e32 v93, 0xbfb8aa3b, v85
	v_mul_f32_e32 v94, 0xbfb8aa3b, v86
	v_mul_f32_e32 v95, 0xbfb8aa3b, v87
	v_mul_f32_e32 v96, 0xbfb8aa3b, v88
	v_mul_f32_e32 v97, 0xbfb8aa3b, v89
	v_mul_f32_e32 v98, 0xbfb8aa3b, v90
	v_mul_f32_e32 v99, 0xbfb8aa3b, v91
	v_exp_f32_e32 v92, v92
	v_exp_f32_e32 v93, v93
	v_exp_f32_e32 v94, v94
	v_exp_f32_e32 v95, v95
	v_exp_f32_e32 v96, v96
	v_exp_f32_e32 v97, v97
	v_exp_f32_e32 v98, v98
	v_exp_f32_e32 v99, v99
	v_add_f32_e32 v92, 1.0, v92
	v_add_f32_e32 v93, 1.0, v93
	v_add_f32_e32 v94, 1.0, v94
	v_add_f32_e32 v95, 1.0, v95
	v_add_f32_e32 v96, 1.0, v96
	v_add_f32_e32 v97, 1.0, v97
	v_add_f32_e32 v98, 1.0, v98
	v_add_f32_e32 v99, 1.0, v99
	v_rcp_f32_e32 v92, v92
	v_rcp_f32_e32 v93, v93
	v_rcp_f32_e32 v94, v94
	v_rcp_f32_e32 v95, v95
	v_rcp_f32_e32 v96, v96
	v_rcp_f32_e32 v97, v97
	v_rcp_f32_e32 v98, v98
	v_rcp_f32_e32 v99, v99
	v_mul_f32_e32 v84, v92, v84
	v_mul_f32_e32 v85, v93, v85
	v_mul_f32_e32 v86, v94, v86
	v_mul_f32_e32 v87, v95, v87
	v_mul_f32_e32 v88, v96, v88
	v_mul_f32_e32 v89, v97, v89
	v_mul_f32_e32 v90, v98, v90
	v_mul_f32_e32 v91, v99, v91
	v_mul_f32_e32 v230, v230, v235
	v_mul_f32_e32 v231, v231, v235
	v_mul_f32_e32 v232, v232, v235
	v_mul_f32_e32 v233, v233, v235
	v_mul_f32_e32 v240, v240, v235
	v_mul_f32_e32 v241, v241, v235
	v_mul_f32_e32 v242, v242, v235
	v_mul_f32_e32 v243, v243, v235
	v_mul_f32_e32 v252, v231, v231
	v_mul_f32_e32 v253, v233, v233
	v_fmac_f32_e32 v252, v230, v230
	v_fmac_f32_e32 v253, v232, v232
	v_add_f32_e32 v251, v252, v253
	v_mul_f32_e32 v253, v241, v241
	v_fmac_f32_e32 v253, v240, v240
	v_mul_f32_e32 v252, v243, v243
	v_add_f32_e32 v251, v253, v251
	v_fmac_f32_e32 v252, v242, v242
	v_add_f32_e32 v251, v252, v251
	v_mul_f32_e32 v84, v84, v230
	v_mul_f32_e32 v85, v85, v231
	v_mul_f32_e32 v86, v86, v232
	v_mul_f32_e32 v87, v87, v233
	v_mul_f32_e32 v88, v88, v240
	v_mul_f32_e32 v89, v89, v241
	v_mul_f32_e32 v90, v90, v242
	v_mul_f32_e32 v91, v91, v243
	v_cvt_pk_bf16_f32 v60, v84, v85
	v_cvt_pk_bf16_f32 v61, v86, v87
	v_cvt_pk_bf16_f32 v62, v88, v89
	v_cvt_pk_bf16_f32 v63, v90, v91
	v_or_b32_e32 v252, 64, v180
	global_store_dwordx4 v252, v[60:63], s[16:17]
	v_add_f32_e32 v250, v250, v251
	ds_bpermute_b32 v251, v144, v250
	s_waitcnt lgkmcnt(0)
	v_add_f32_e32 v2, v250, v251
	v_mov_b32_e32 v3, v2
	s_nop 1
	v_permlane32_swap_b32_e32 v2, v3
	s_and_saveexec_b64 s[10:11], s[6:7]
	v_add_f32_e32 v2, v2, v3
	ds_write_b32 v179, v2
	s_branch .LBB0_496
